# attention A: next-item Q prefetch issued at DILP/MEM item start into v[96:127] (hidden behind the tile loop) instead of at finalize
# speedup vs baseline: 1.0356x; 1.0053x over previous
.LBB0_356:
	v_and_b32_e32 v14, 31, v169
	v_lshrrev_b32_e32 v15, 5, v169
	v_lshlrev_b32_e32 v2, 2, v169
	v_and_b32_e32 v2, 12, v2
	v_bfe_u32 v3, v169, 2, 2
	v_or_b32_e32 v2, v2, v3
	v_xor_b32_e32 v250, v15, v2
	v_lshlrev_b32_e32 v250, 4, v250
	v_lshl_add_u32 v248, v14, 8, v250
	v_lshl_or_b32 v14, v15, 2, v3
	v_lshlrev_b32_e32 v2, 2, v3
	v_or_b32_e32 v2, v2, v15
	v_bfe_u32 v250, v169, 1, 1
	v_lshrrev_b32_e32 v251, 3, v169
	v_and_or_b32 v250, v251, 2, v250
	v_xor_b32_e32 v250, v250, v2
	v_lshlrev_b32_e32 v250, 4, v250
	v_lshl_add_u32 v250, v14, 8, v250
	v_lshlrev_b32_e32 v251, 3, v169
	v_and_b32_e32 v251, 8, v251
	v_add_u32_e32 v249, v250, v251
	v_add_u32_e32 v249, 0x2000, v249
	v_mov_b32_e32 v14, v1
	v_mov_b32_e32 v15, v1
	v_mov_b32_e32 v0, v1
	v_mov_b32_e32 v2, v1
	v_mov_b32_e32 v3, v1
	v_mov_b32_e32 v4, v1
	v_mov_b32_e32 v5, v1
	v_mov_b32_e32 v6, v1
	v_mov_b32_e32 v7, v1
	v_mov_b32_e32 v8, v1
	v_mov_b32_e32 v9, v1
	v_mov_b32_e32 v10, v1
	v_mov_b32_e32 v11, v1
	v_mov_b32_e32 v12, v1
	v_mov_b32_e32 v13, v1
	v_mov_b64_e32 v[64:65], v[14:15]
	v_mov_b64_e32 v[48:49], v[14:15]
	v_mov_b64_e32 v[32:33], v[14:15]
	s_waitcnt vmcnt(0) lgkmcnt(0)
	v_mov_b64_e32 v[82:83], v[124:125]
	v_mov_b64_e32 v[86:87], v[120:121]
	v_mov_b64_e32 v[90:91], v[116:117]
	v_mov_b64_e32 v[130:131], v[114:115]
	v_mov_b64_e32 v[134:135], v[110:111]
	v_mov_b64_e32 v[138:139], v[106:107]
	v_mov_b64_e32 v[142:143], v[102:103]
	v_mov_b64_e32 v[146:147], v[98:99]
	s_bitcmp1_b32 s56, 0
	v_mov_b64_e32 v[62:63], v[12:13]
	v_mov_b64_e32 v[60:61], v[10:11]
	v_mov_b64_e32 v[58:59], v[8:9]
	v_mov_b64_e32 v[56:57], v[6:7]
	v_mov_b64_e32 v[54:55], v[4:5]
	v_mov_b64_e32 v[52:53], v[2:3]
	v_mov_b64_e32 v[50:51], v[0:1]
	v_mov_b64_e32 v[46:47], v[12:13]
	v_mov_b64_e32 v[44:45], v[10:11]
	v_mov_b64_e32 v[42:43], v[8:9]
	v_mov_b64_e32 v[40:41], v[6:7]
	v_mov_b64_e32 v[38:39], v[4:5]
	v_mov_b64_e32 v[36:37], v[2:3]
	v_mov_b64_e32 v[34:35], v[0:1]
	v_mov_b64_e32 v[30:31], v[12:13]
	v_mov_b64_e32 v[28:29], v[10:11]
	v_mov_b64_e32 v[26:27], v[8:9]
	v_mov_b64_e32 v[24:25], v[6:7]
	v_mov_b64_e32 v[22:23], v[4:5]
	v_mov_b64_e32 v[20:21], v[2:3]
	v_mov_b64_e32 v[18:19], v[0:1]
	v_mov_b64_e32 v[16:17], v[14:15]
	v_mov_b64_e32 v[84:85], v[126:127]
	v_mov_b64_e32 v[88:89], v[122:123]
	v_mov_b64_e32 v[92:93], v[118:119]
	v_mov_b64_e32 v[128:129], v[112:113]
	v_mov_b64_e32 v[132:133], v[108:109]
	v_mov_b64_e32 v[136:137], v[104:105]
	v_mov_b64_e32 v[140:141], v[100:101]
	v_mov_b64_e32 v[144:145], v[96:97]
	s_cselect_b64 s[80:81], -1, 0
	s_mov_b32 s77, 0
	v_mov_b32_e32 v199, 0xc61c4000
	v_mov_b32_e32 v198, 0
	s_mov_b64 s[26:27], s[4:5]
	s_mov_b64 s[12:13], s[86:87]
	v_mov_b32_e32 v94, v182
	v_mov_b32_e32 v183, v171
	s_mov_b32 s98, s61
	s_mov_b32 s50, s68
	s_mov_b32 s67, s51
	s_mov_b32 s69, s52
	s_mov_b32 s65, s57
	s_mov_b32 s53, s70
	s_mov_b32 s71, s60
	s_mov_b32 s19, s54
	s_mov_b32 s63, s55
	s_mov_b32 s59, s64
	v_mov_b64_e32 v[14:15], v[12:13]
	v_mov_b64_e32 v[12:13], v[10:11]
	v_mov_b64_e32 v[10:11], v[8:9]
	v_mov_b64_e32 v[8:9], v[6:7]
	v_mov_b64_e32 v[6:7], v[4:5]
	v_mov_b64_e32 v[4:5], v[2:3]
	v_mov_b64_e32 v[2:3], v[0:1]
	s_cmp_gt_i32 s7, -1
	s_cbranch_scc0 .Lpf_skip_d
	s_add_i32 s16, s7, s82
	s_add_i32 s17, s16, -3
	s_cmp_gt_i32 s16, 2
	s_cselect_b32 s16, s17, s16
	s_cmp_eq_u32 s16, 0
	s_cbranch_scc1 .Lpf_na_d
	s_cmp_eq_u32 s16, 1
	s_cbranch_scc1 .Lpf_mem_d
	s_mul_hi_i32 s16, s62, 0x2aaaaaab
	s_lshr_b32 s17, s16, 31
	s_ashr_i32 s16, s16, 7
	s_add_i32 s16, s16, s17
	s_add_i32 s79, s16, 1
	s_mulk_i32 s16, 0x300
	s_sub_i32 s16, s62, s16
	s_mul_i32 s17, s16, 0x2aab
	s_lshr_b32 s28, s17, 31
	s_ashr_i32 s17, s17, 19
	s_add_i32 s17, s17, s28
	s_mul_i32 s28, s17, 48
	s_sub_i32 s16, s16, s28
	s_sext_i32_i16 s21, s16
	s_and_b32 s32, s21, 7
	s_sext_i32_i16 s16, s17
	s_cmp_lg_u32 s79, 2
	s_cbranch_scc0 .Lpf_d2_d
	s_add_i32 s17, s62, 0x2ff
	s_lshr_b32 s28, s32, 1
	s_and_b32 s29, s21, 1
	s_cmpk_lt_u32 s17, 0x5ff
	s_cselect_b32 s100, s28, 0
	s_cselect_b32 s101, s29, s32
	s_ashr_i32 s17, s16, 31
	s_lshl_b64 s[28:29], s[16:17], 11
	s_cmp_eq_u32 s79, 0
	v_lshl_add_u32 v68, s101, 8, v173
	v_ashrrev_i32_e32 v69, 31, v68
	s_cselect_b32 s17, 0, 2
	v_lshlrev_b64 v[68:69], s17, v[68:69]
	s_or_b32 s28, s28, s100
	v_lshl_add_u64 v[68:69], s[28:29], 0, v[68:69]
	s_branch .Lpf_d3_d
.Lpf_d2_d:
	s_ashr_i32 s17, s16, 31
	s_lshl_b64 s[16:17], s[16:17], 11
	s_lshl_b32 s28, s32, 1
	s_or_b32 s16, s16, s28
	v_lshl_add_u64 v[68:69], s[16:17], 0, v[162:163]
.Lpf_d3_d:
	s_lshl_b32 s16, s21, 4
	s_and_b32 s16, s16, 0xffffff80
	s_addk_i32 s16, 0xc00
	s_branch .Lpf_go_d
.Lpf_mem_d:
	s_ashr_i32 s16, s62, 5
	s_lshl_b32 s28, s62, 8
	s_ashr_i32 s17, s16, 31
	s_and_b32 s28, s28, 0x700
	s_lshl_b64 s[16:17], s[16:17], 11
	v_add_u32_e32 v0, s28, v173
	v_lshl_add_u64 v[68:69], s[16:17], 0, v[0:1]
	s_lshl_b32 s16, s62, 4
	s_and_b32 s16, s16, 0x180
	s_or_b32 s16, s16, 0x1800
	s_branch .Lpf_go_d
.Lpf_na_d:
	s_mul_hi_i32 s16, s62, 0x2aaaaaab
	s_lshr_b32 s17, s16, 31
	s_ashr_i32 s16, s16, 3
	s_add_i32 s16, s16, s17
	s_mul_i32 s17, s16, 48
	s_sub_i32 s28, s62, s17
	s_lshl_b32 s29, s28, 2
	s_ashr_i32 s17, s16, 31
	s_lshl_b64 s[16:17], s[16:17], 11
	v_and_or_b32 v0, s29, 28, v194
	v_lshlrev_b32_e32 v0, 6, v0
	v_lshl_add_u64 v[68:69], s[16:17], 0, v[158:159]
	s_lshl_b32 s16, s28, 4
	v_lshl_add_u64 v[68:69], v[68:69], 0, v[0:1]
	s_and_b32 s16, s16, 0xffffff80
.Lpf_go_d:
	v_mov_b64_e32 v[70:71], s[96:97]
	v_mad_u64_u32 v[70:71], s[28:29], v68, s43, v[70:71]
	v_mov_b32_e32 v0, v71
	v_mad_u64_u32 v[68:69], s[28:29], v69, s43, v[0:1]
	v_mov_b32_e32 v71, v68
	s_ashr_i32 s17, s16, 31
	v_lshl_add_u64 v[68:69], s[16:17], 1, v[70:71]
	v_lshl_add_u64 v[68:69], v[68:69], 0, v[160:161]
	global_load_dwordx4 v[124:127], v[68:69], off
	global_load_dwordx4 v[120:123], v[68:69], off offset:32
	global_load_dwordx4 v[116:119], v[68:69], off offset:64
	global_load_dwordx4 v[112:115], v[68:69], off offset:96
	global_load_dwordx4 v[108:111], v[68:69], off offset:128
	global_load_dwordx4 v[104:107], v[68:69], off offset:160
	global_load_dwordx4 v[100:103], v[68:69], off offset:192
	global_load_dwordx4 v[96:99], v[68:69], off offset:224
.Lpf_skip_d:
	s_branch .LBB0_358
.LBB0_357:
	s_add_i32 s0, s59, 1
	s_cmp_lg_u32 s0, 6
	s_cselect_b32 s59, s0, 0
	s_add_i32 s77, s77, 1
	s_bitcmp1_b32 s21, 0
	s_waitcnt lgkmcnt(0)
	s_barrier
	s_cselect_b64 s[80:81], -1, 0
	s_add_i32 s75, s75, 32
	s_cmp_eq_u32 s76, s77
	s_cbranch_scc1 .LBB0_415

.LBB0_415:
	v_and_b32_e32 v66, 64, v207
	v_xor_b32_e32 v0, 32, v207
	v_add_u32_e32 v66, 64, v66
	v_cmp_lt_i32_e32 vcc, v0, v66
	s_cmp_gt_i32 s7, -1
	s_nop 0
	v_cndmask_b32_e32 v0, v207, v0, vcc
	v_lshlrev_b32_e32 v0, 2, v0
	ds_bpermute_b32 v68, v0, v198
	s_mov_b32 s74, s35
	s_mov_b32 s35, s34
	s_mov_b32 s34, s78
	s_mov_b64 s[78:79], s[8:9]

.LBB0_441:
	v_and_b32_e32 v14, 31, v169
	v_lshrrev_b32_e32 v15, 5, v169
	v_lshlrev_b32_e32 v2, 2, v169
	v_and_b32_e32 v2, 12, v2
	v_bfe_u32 v3, v169, 2, 2
	v_or_b32_e32 v2, v2, v3
	v_xor_b32_e32 v250, v15, v2
	v_lshlrev_b32_e32 v250, 4, v250
	v_lshl_add_u32 v204, v14, 8, v250
	v_lshl_or_b32 v14, v15, 2, v3
	v_lshlrev_b32_e32 v2, 2, v3
	v_or_b32_e32 v2, v2, v15
	v_bfe_u32 v250, v169, 1, 1
	v_lshrrev_b32_e32 v251, 3, v169
	v_and_or_b32 v250, v251, 2, v250
	v_xor_b32_e32 v250, v250, v2
	v_lshlrev_b32_e32 v250, 4, v250
	v_lshl_add_u32 v250, v14, 8, v250
	v_lshlrev_b32_e32 v251, 3, v169
	v_and_b32_e32 v251, 8, v251
	v_add_u32_e32 v215, v250, v251
	v_add_u32_e32 v215, 0x2000, v215
	v_mov_b32_e32 v14, v1
	v_mov_b32_e32 v15, v1
	v_mov_b32_e32 v0, v1
	s_waitcnt lgkmcnt(0)
	v_mov_b32_e32 v2, v1
	v_mov_b32_e32 v3, v1
	v_mov_b32_e32 v4, v1
	v_mov_b32_e32 v5, v1
	v_mov_b32_e32 v6, v1
	v_mov_b32_e32 v7, v1
	v_mov_b32_e32 v8, v1
	v_mov_b32_e32 v9, v1
	v_mov_b32_e32 v10, v1
	v_mov_b32_e32 v11, v1
	v_mov_b32_e32 v12, v1
	v_mov_b32_e32 v13, v1
	v_mov_b64_e32 v[64:65], v[14:15]
	v_mov_b64_e32 v[48:49], v[14:15]
	v_mov_b64_e32 v[32:33], v[14:15]
	s_waitcnt vmcnt(0)
	v_mov_b64_e32 v[82:83], v[124:125]
	v_mov_b64_e32 v[86:87], v[120:121]
	v_mov_b64_e32 v[90:91], v[116:117]
	v_mov_b64_e32 v[130:131], v[114:115]
	v_mov_b64_e32 v[134:135], v[110:111]
	v_mov_b64_e32 v[138:139], v[106:107]
	v_mov_b64_e32 v[142:143], v[102:103]
	v_mov_b64_e32 v[146:147], v[98:99]
	s_bitcmp1_b32 s56, 0
	v_mov_b64_e32 v[62:63], v[12:13]
	v_mov_b64_e32 v[60:61], v[10:11]
	v_mov_b64_e32 v[58:59], v[8:9]
	v_mov_b64_e32 v[56:57], v[6:7]
	v_mov_b64_e32 v[54:55], v[4:5]
	v_mov_b64_e32 v[52:53], v[2:3]
	v_mov_b64_e32 v[50:51], v[0:1]
	v_mov_b64_e32 v[46:47], v[12:13]
	v_mov_b64_e32 v[44:45], v[10:11]
	v_mov_b64_e32 v[42:43], v[8:9]
	v_mov_b64_e32 v[40:41], v[6:7]
	v_mov_b64_e32 v[38:39], v[4:5]
	v_mov_b64_e32 v[36:37], v[2:3]
	v_mov_b64_e32 v[34:35], v[0:1]
	v_mov_b64_e32 v[30:31], v[12:13]
	v_mov_b64_e32 v[28:29], v[10:11]
	v_mov_b64_e32 v[26:27], v[8:9]
	v_mov_b64_e32 v[24:25], v[6:7]
	v_mov_b64_e32 v[22:23], v[4:5]
	v_mov_b64_e32 v[20:21], v[2:3]
	v_mov_b64_e32 v[18:19], v[0:1]
	v_mov_b64_e32 v[16:17], v[14:15]
	v_mov_b64_e32 v[84:85], v[126:127]
	v_mov_b64_e32 v[88:89], v[122:123]
	v_mov_b64_e32 v[92:93], v[118:119]
	v_mov_b64_e32 v[128:129], v[112:113]
	v_mov_b64_e32 v[132:133], v[108:109]
	v_mov_b64_e32 v[136:137], v[104:105]
	v_mov_b64_e32 v[140:141], v[100:101]
	v_mov_b64_e32 v[144:145], v[96:97]
	s_cselect_b64 s[10:11], -1, 0
	v_mov_b32_e32 v199, 0xc61c4000
	v_mov_b32_e32 v198, 0
	s_mov_b32 s24, 8
	s_mov_b64 s[26:27], s[4:5]
	s_mov_b64 s[12:13], s[86:87]
	v_mov_b32_e32 v94, v182
	v_mov_b32_e32 v183, v171
	s_mov_b32 s98, s61
	s_mov_b32 s50, s68
	s_mov_b32 s67, s51
	s_mov_b32 s69, s52
	s_mov_b32 s65, s57
	s_mov_b32 s53, s70
	s_mov_b32 s71, s60
	s_mov_b32 s19, s54
	s_mov_b32 s63, s55
	s_mov_b32 s59, s64
	v_mov_b64_e32 v[14:15], v[12:13]
	v_mov_b64_e32 v[12:13], v[10:11]
	v_mov_b64_e32 v[10:11], v[8:9]
	v_mov_b64_e32 v[8:9], v[6:7]
	v_mov_b64_e32 v[6:7], v[4:5]
	v_mov_b64_e32 v[4:5], v[2:3]
	v_mov_b64_e32 v[2:3], v[0:1]
	s_cmp_gt_i32 s7, -1
	s_cbranch_scc0 .Lpf_skip_m
	s_add_i32 s0, s7, s82
	s_add_i32 s1, s0, -3
	s_cmp_gt_i32 s0, 2
	s_cselect_b32 s0, s1, s0
	s_cmp_eq_u32 s0, 0
	s_cbranch_scc1 .Lpf_na_m
	s_cmp_eq_u32 s0, 1
	s_cbranch_scc1 .Lpf_mem_m
	s_mul_hi_i32 s0, s62, 0x2aaaaaab
	s_lshr_b32 s1, s0, 31
	s_ashr_i32 s0, s0, 7
	s_add_i32 s0, s0, s1
	s_add_i32 s16, s0, 1
	s_mulk_i32 s0, 0x300
	s_sub_i32 s0, s62, s0
	s_mul_i32 s1, s0, 0x2aab
	s_lshr_b32 s8, s1, 31
	s_ashr_i32 s1, s1, 19
	s_add_i32 s1, s1, s8
	s_mul_i32 s8, s1, 48
	s_sub_i32 s0, s0, s8
	s_sext_i32_i16 s14, s0
	s_and_b32 s15, s14, 7
	s_sext_i32_i16 s0, s1
	s_cmp_lg_u32 s16, 2
	s_cbranch_scc0 .Lpf_d2_m
	s_add_i32 s1, s62, 0x2ff
	s_lshr_b32 s8, s15, 1
	s_and_b32 s9, s14, 1
	s_cmpk_lt_u32 s1, 0x5ff
	s_cselect_b32 s28, s8, 0
	s_cselect_b32 s29, s9, s15
	s_ashr_i32 s1, s0, 31
	s_lshl_b64 s[8:9], s[0:1], 11
	s_cmp_eq_u32 s16, 0
	v_lshl_add_u32 v68, s29, 8, v173
	v_ashrrev_i32_e32 v69, 31, v68
	s_cselect_b32 s1, 0, 2
	v_lshlrev_b64 v[68:69], s1, v[68:69]
	s_or_b32 s8, s8, s28
	v_lshl_add_u64 v[68:69], s[8:9], 0, v[68:69]
	s_branch .Lpf_d3_m
.Lpf_d2_m:
	s_ashr_i32 s1, s0, 31
	s_lshl_b64 s[0:1], s[0:1], 11
	s_lshl_b32 s8, s15, 1
	s_or_b32 s0, s0, s8
	v_lshl_add_u64 v[68:69], s[0:1], 0, v[162:163]
.Lpf_d3_m:
	s_lshl_b32 s0, s14, 4
	s_and_b32 s0, s0, 0xffffff80
	s_addk_i32 s0, 0xc00
	s_branch .Lpf_go_m
.Lpf_mem_m:
	s_ashr_i32 s0, s62, 5
	s_lshl_b32 s8, s62, 8
	s_ashr_i32 s1, s0, 31
	s_and_b32 s8, s8, 0x700
	s_lshl_b64 s[0:1], s[0:1], 11
	v_add_u32_e32 v0, s8, v173
	v_lshl_add_u64 v[68:69], s[0:1], 0, v[0:1]
	s_lshl_b32 s0, s62, 4
	s_and_b32 s0, s0, 0x180
	s_or_b32 s0, s0, 0x1800
	s_branch .Lpf_go_m
.Lpf_na_m:
	s_mul_hi_i32 s0, s62, 0x2aaaaaab
	s_lshr_b32 s1, s0, 31
	s_ashr_i32 s0, s0, 3
	s_add_i32 s0, s0, s1
	s_mul_i32 s1, s0, 48
	s_sub_i32 s8, s62, s1
	s_lshl_b32 s9, s8, 2
	s_ashr_i32 s1, s0, 31
	s_lshl_b64 s[0:1], s[0:1], 11
	v_and_or_b32 v0, s9, 28, v194
	v_lshlrev_b32_e32 v0, 6, v0
	v_lshl_add_u64 v[68:69], s[0:1], 0, v[158:159]
	s_lshl_b32 s0, s8, 4
	v_lshl_add_u64 v[68:69], v[68:69], 0, v[0:1]
	s_and_b32 s0, s0, 0xffffff80
.Lpf_go_m:
	v_mov_b64_e32 v[70:71], s[96:97]
	v_mad_u64_u32 v[70:71], s[8:9], v68, s43, v[70:71]
	v_mov_b32_e32 v0, v71
	v_mad_u64_u32 v[68:69], s[8:9], v69, s43, v[0:1]
	v_mov_b32_e32 v71, v68
	s_ashr_i32 s1, s0, 31
	v_lshl_add_u64 v[68:69], s[0:1], 1, v[70:71]
	v_lshl_add_u64 v[68:69], v[68:69], 0, v[160:161]
	global_load_dwordx4 v[124:127], v[68:69], off
	global_load_dwordx4 v[120:123], v[68:69], off offset:32
	global_load_dwordx4 v[116:119], v[68:69], off offset:64
	global_load_dwordx4 v[112:115], v[68:69], off offset:96
	global_load_dwordx4 v[108:111], v[68:69], off offset:128
	global_load_dwordx4 v[104:107], v[68:69], off offset:160
	global_load_dwordx4 v[100:103], v[68:69], off offset:192
	global_load_dwordx4 v[96:99], v[68:69], off offset:224
.Lpf_skip_m:
	s_mov_b32 s21, 1
	s_and_b64 vcc, exec, s[10:11]
	s_cbranch_vccnz .LBB0_475
	s_branch .LBB0_443

.LBB0_481:
	s_add_i32 s0, s59, 1
	s_cmp_lg_u32 s0, 6
	s_cselect_b32 s59, s0, 0
	s_bitcmp1_b32 s21, 0
	s_waitcnt lgkmcnt(0)
	s_barrier
	s_cselect_b64 s[10:11], -1, 0
	s_add_i32 s24, s24, -1
	s_cmp_eq_u32 s24, 0
	s_cbranch_scc0 .LBB0_442
	ds_bpermute_b32 v69, v200, v68
.LBB0_496:
	s_waitcnt lgkmcnt(0)
	v_add_f32_e32 v0, v68, v69
	v_rcp_f32_e32 v66, v0
	s_ashr_i32 s0, s58, 5
	s_lshl_b32 s10, s58, 8
	s_ashr_i32 s1, s0, 31
	s_and_b32 s10, s10, 0x700
	s_lshl_b64 s[0:1], s[0:1], 11
	s_add_i32 s10, s10, s31
	v_pk_mul_f32 v[34:35], v[34:35], v[66:67] op_sel_hi:[1,0]
	v_pk_mul_f32 v[36:37], v[36:37], v[66:67] op_sel_hi:[1,0]
	s_add_u32 s16, s0, s10
	v_cvt_pk_bf16_f32 v34, v34, v35
	v_cvt_pk_bf16_f32 v35, v36, v37
	v_pk_mul_f32 v[36:37], v[38:39], v[66:67] op_sel_hi:[1,0]
	v_pk_mul_f32 v[38:39], v[40:41], v[66:67] op_sel_hi:[1,0]
	s_addc_u32 s0, s1, 0
	v_cvt_pk_bf16_f32 v36, v36, v37
	v_cvt_pk_bf16_f32 v37, v38, v39
	s_lshl_b32 s1, s58, 5
	v_pk_mul_f32 v[50:51], v[50:51], v[66:67] op_sel_hi:[1,0]
	v_pk_mul_f32 v[52:53], v[52:53], v[66:67] op_sel_hi:[1,0]
	ds_write2_b64 v197, v[34:35], v[36:37] offset0:8 offset1:10
	v_pk_mul_f32 v[34:35], v[42:43], v[66:67] op_sel_hi:[1,0]
	v_pk_mul_f32 v[36:37], v[44:45], v[66:67] op_sel_hi:[1,0]
	s_and_b32 s10, s1, 0x300
	v_cvt_pk_bf16_f32 v50, v50, v51
	v_cvt_pk_bf16_f32 v51, v52, v53
	v_pk_mul_f32 v[52:53], v[54:55], v[66:67] op_sel_hi:[1,0]
	v_pk_mul_f32 v[54:55], v[56:57], v[66:67] op_sel_hi:[1,0]
	v_cvt_pk_bf16_f32 v34, v34, v35
	v_cvt_pk_bf16_f32 v35, v36, v37
	v_pk_mul_f32 v[36:37], v[46:47], v[66:67] op_sel_hi:[1,0]
	v_pk_mul_f32 v[38:39], v[48:49], v[66:67] op_sel_hi:[1,0]
	s_add_u32 s14, s96, s10
	v_cvt_pk_bf16_f32 v52, v52, v53
	v_cvt_pk_bf16_f32 v53, v54, v55
	v_cvt_pk_bf16_f32 v36, v36, v37
	v_cvt_pk_bf16_f32 v37, v38, v39
	s_addc_u32 s15, s97, 0
	ds_write2_b64 v197, v[50:51], v[52:53] offset1:2
	v_pk_mul_f32 v[50:51], v[58:59], v[66:67] op_sel_hi:[1,0]
	v_pk_mul_f32 v[52:53], v[60:61], v[66:67] op_sel_hi:[1,0]
	v_pk_mul_f32 v[54:55], v[64:65], v[66:67] op_sel_hi:[1,0]
	ds_write2_b64 v197, v[34:35], v[36:37] offset0:12 offset1:14
	v_or_b32_e32 v64, s16, v164
	v_mov_b64_e32 v[34:35], s[14:15]
	v_cvt_pk_bf16_f32 v50, v50, v51
	v_cvt_pk_bf16_f32 v51, v52, v53
	v_pk_mul_f32 v[52:53], v[62:63], v[66:67] op_sel_hi:[1,0]
	v_mad_u64_u32 v[36:37], s[14:15], v64, s43, v[34:35]
	v_cvt_pk_bf16_f32 v52, v52, v53
	v_cvt_pk_bf16_f32 v53, v54, v55
	v_mad_i32_i24 v37, s0, v211, v37
	s_mov_b64 s[24:25], 0x3400
	ds_write2_b64 v197, v[50:51], v[52:53] offset0:4 offset1:6
	v_lshl_add_u64 v[42:43], v[36:37], 0, s[24:25]
	v_lshlrev_b32_e32 v0, 1, v166
	s_waitcnt lgkmcnt(0)
	v_lshl_add_u64 v[36:37], v[42:43], 0, v[0:1]
	flat_load_dwordx4 v[50:53], v[36:37]
	v_or_b32_e32 v72, s16, v168
	v_mad_u64_u32 v[36:37], s[14:15], v72, s43, v[34:35]
	v_mad_i32_i24 v37, s0, v211, v37
	v_lshl_add_u64 v[48:49], v[36:37], 0, s[24:25]
	v_lshl_add_u64 v[36:37], v[48:49], 0, v[0:1]
	flat_load_dwordx4 v[68:71], v[36:37]
	v_or_b32_e32 v56, s16, v170
	v_or_b32_e32 v54, s16, v172
	v_mad_u64_u32 v[38:39], s[14:15], v56, s43, v[34:35]
	v_mad_u64_u32 v[34:35], s[14:15], v54, s43, v[34:35]
	v_mad_i32_i24 v39, s0, v211, v39
	v_mad_i32_i24 v35, s0, v211, v35
	v_lshl_add_u64 v[44:45], v[38:39], 0, s[24:25]
	v_lshl_add_u64 v[46:47], v[34:35], 0, s[24:25]
	v_add_u32_e32 v58, v185, v186
	v_lshl_add_u64 v[34:35], v[44:45], 0, v[0:1]
	v_lshl_add_u64 v[36:37], v[46:47], 0, v[0:1]
	ds_read_b128 v[60:63], v58
	flat_load_dwordx4 v[38:41], v[34:35]
	s_nop 0
	flat_load_dwordx4 v[34:37], v[36:37]
	v_lshlrev_b32_e32 v232, 1, v174
	v_mov_b32_e32 v233, 0
	v_lshl_add_u64 v[234:235], v[42:43], 0, v[232:233]
	global_load_dwordx4 v[216:219], v[234:235], off
	v_lshl_add_u64 v[234:235], v[48:49], 0, v[232:233]
	global_load_dwordx4 v[220:223], v[234:235], off
	v_lshl_add_u64 v[234:235], v[44:45], 0, v[232:233]
	global_load_dwordx4 v[224:227], v[234:235], off
	v_lshl_add_u64 v[234:235], v[46:47], 0, v[232:233]
	global_load_dwordx4 v[228:231], v[234:235], off
	v_mov_b32_e32 v65, s0
	s_mov_b32 s11, s99
	v_mov_b32_e32 v73, s0
	s_waitcnt lgkmcnt(0)
	v_lshlrev_b32_e32 v74, 16, v60
	v_and_b32_e32 v75, 0xffff0000, v60
	v_lshlrev_b32_e32 v60, 16, v61
	v_and_b32_e32 v61, 0xffff0000, v61
	v_pk_mul_f32 v[18:19], v[18:19], v[66:67] op_sel_hi:[1,0]
	v_pk_mul_f32 v[20:21], v[20:21], v[66:67] op_sel_hi:[1,0]
	v_pk_mul_f32 v[2:3], v[2:3], v[66:67] op_sel_hi:[1,0]
	v_pk_mul_f32 v[4:5], v[4:5], v[66:67] op_sel_hi:[1,0]
	v_cvt_pk_bf16_f32 v18, v18, v19
	v_cvt_pk_bf16_f32 v19, v20, v21
	v_pk_mul_f32 v[20:21], v[22:23], v[66:67] op_sel_hi:[1,0]
	v_pk_mul_f32 v[22:23], v[24:25], v[66:67] op_sel_hi:[1,0]
	v_cvt_pk_bf16_f32 v2, v2, v3
	v_cvt_pk_bf16_f32 v3, v4, v5
	v_pk_mul_f32 v[4:5], v[6:7], v[66:67] op_sel_hi:[1,0]
	v_pk_mul_f32 v[6:7], v[8:9], v[66:67] op_sel_hi:[1,0]
	v_cvt_pk_bf16_f32 v20, v20, v21
	v_cvt_pk_bf16_f32 v21, v22, v23
	v_cvt_pk_bf16_f32 v4, v4, v5
	v_cvt_pk_bf16_f32 v5, v6, v7
	v_pk_mul_f32 v[22:23], v[32:33], v[66:67] op_sel_hi:[1,0]
	v_pk_mul_f32 v[6:7], v[16:17], v[66:67] op_sel_hi:[1,0]
	s_waitcnt vmcnt(0)
	v_lshlrev_b32_e32 v76, 16, v50
	v_and_b32_e32 v77, 0xffff0000, v50
	v_mul_f32_e32 v55, 0xbfb8aa3b, v76
	v_mul_f32_e32 v57, 0xbfb8aa3b, v77
	v_exp_f32_e32 v55, v55
	v_exp_f32_e32 v57, v57
	v_lshlrev_b32_e32 v50, 16, v51
	v_and_b32_e32 v51, 0xffff0000, v51
	v_add_f32_e32 v55, 1.0, v55
	v_add_f32_e32 v57, 1.0, v57
	v_rcp_f32_e32 v78, v55
	v_rcp_f32_e32 v79, v57
	v_mul_f32_e32 v55, 0xbfb8aa3b, v51
	v_mul_f32_e32 v59, 0xbfb8aa3b, v50
	v_exp_f32_e32 v55, v55
	v_exp_f32_e32 v59, v59
	v_pk_mul_f32 v[76:77], v[78:79], v[76:77]
	v_add_f32_e32 v55, 1.0, v55
	v_pk_mul_f32 v[74:75], v[76:77], v[74:75]
	v_lshlrev_b32_e32 v76, 16, v52
	v_and_b32_e32 v77, 0xffff0000, v52
	v_mul_f32_e32 v52, 0xbfb8aa3b, v76
	v_add_f32_e32 v57, 1.0, v59
	v_rcp_f32_e32 v79, v55
	v_exp_f32_e32 v52, v52
	v_mul_f32_e32 v55, 0xbfb8aa3b, v77
	v_rcp_f32_e32 v78, v57
	v_exp_f32_e32 v55, v55
	v_add_f32_e32 v52, 1.0, v52
	v_pk_mul_f32 v[50:51], v[78:79], v[50:51]
	v_rcp_f32_e32 v78, v52
	v_add_f32_e32 v52, 1.0, v55
	v_rcp_f32_e32 v79, v52
	v_lshlrev_b32_e32 v52, 16, v53
	v_and_b32_e32 v53, 0xffff0000, v53
	v_mul_f32_e32 v55, 0xbfb8aa3b, v52
	v_exp_f32_e32 v55, v55
	v_mul_f32_e32 v57, 0xbfb8aa3b, v53
	v_exp_f32_e32 v57, v57
	v_pk_mul_f32 v[76:77], v[78:79], v[76:77]
	v_add_f32_e32 v55, 1.0, v55
	v_rcp_f32_e32 v78, v55
	v_add_f32_e32 v55, 1.0, v57
	v_rcp_f32_e32 v79, v55
	v_pk_mul_f32 v[50:51], v[50:51], v[60:61]
	v_lshlrev_b32_e32 v60, 16, v62
	v_and_b32_e32 v61, 0xffff0000, v62
	v_pk_mul_f32 v[76:77], v[76:77], v[60:61]
	v_lshlrev_b32_e32 v60, 16, v63
	v_and_b32_e32 v61, 0xffff0000, v63
	v_pk_mul_f32 v[52:53], v[78:79], v[52:53]
	v_cvt_pk_bf16_f32 v62, v76, v77
	v_pk_mul_f32 v[52:53], v[52:53], v[60:61]
	v_cvt_pk_bf16_f32 v61, v50, v51
	v_lshlrev_b64 v[50:51], 12, v[64:65]
	v_lshlrev_b32_e32 v64, 16, v68
	v_cvt_pk_bf16_f32 v63, v52, v53
	v_and_b32_e32 v65, 0xffff0000, v68
	v_mul_f32_e32 v53, 0xbfb8aa3b, v64
	v_exp_f32_e32 v55, v53
	v_mul_f32_e32 v53, 0xbfb8aa3b, v65
	v_exp_f32_e32 v57, v53
	v_cvt_pk_bf16_f32 v60, v74, v75
	v_add_f32_e32 v55, 1.0, v55
	v_rcp_f32_e32 v74, v55
	v_add_f32_e32 v55, 1.0, v57
	v_lshlrev_b32_e32 v68, 16, v69
	v_rcp_f32_e32 v75, v55
	v_and_b32_e32 v69, 0xffff0000, v69
	v_mul_f32_e32 v55, 0xbfb8aa3b, v68
	v_lshl_add_u64 v[50:51], s[90:91], 0, v[50:51]
	v_exp_f32_e32 v55, v55
	v_mul_f32_e32 v57, 0xbfb8aa3b, v69
	v_lshl_add_u64 v[50:51], v[50:51], 0, s[10:11]
	v_exp_f32_e32 v57, v57
	v_lshl_add_u64 v[50:51], v[50:51], 0, v[0:1]
	flat_store_dwordx4 v[50:51], v[60:63] offset:3072
	ds_read_b128 v[60:63], v58 offset:1152
	v_add_f32_e32 v55, 1.0, v55
	v_pk_mul_f32 v[64:65], v[74:75], v[64:65]
	v_rcp_f32_e32 v74, v55
	v_add_f32_e32 v55, 1.0, v57
	v_rcp_f32_e32 v75, v55
	s_waitcnt lgkmcnt(0)
	v_lshlrev_b32_e32 v52, 16, v60
	v_and_b32_e32 v53, 0xffff0000, v60
	v_pk_mul_f32 v[52:53], v[64:65], v[52:53]
	v_pk_mul_f32 v[64:65], v[74:75], v[68:69]
	v_lshlrev_b32_e32 v68, 16, v70
	v_and_b32_e32 v69, 0xffff0000, v70
	v_mul_f32_e32 v55, 0xbfb8aa3b, v68
	v_exp_f32_e32 v55, v55
	v_mul_f32_e32 v57, 0xbfb8aa3b, v69
	v_exp_f32_e32 v57, v57
	v_lshlrev_b32_e32 v70, 16, v71
	v_add_f32_e32 v55, 1.0, v55
	v_rcp_f32_e32 v74, v55
	v_add_f32_e32 v55, 1.0, v57
	v_rcp_f32_e32 v75, v55
	v_and_b32_e32 v71, 0xffff0000, v71
	v_mul_f32_e32 v55, 0xbfb8aa3b, v70
	v_exp_f32_e32 v55, v55
	v_mul_f32_e32 v57, 0xbfb8aa3b, v71
	v_exp_f32_e32 v57, v57
	v_pk_mul_f32 v[68:69], v[74:75], v[68:69]
	v_add_f32_e32 v55, 1.0, v55
	v_rcp_f32_e32 v74, v55
	v_add_f32_e32 v55, 1.0, v57
	v_rcp_f32_e32 v75, v55
	v_lshlrev_b32_e32 v60, 16, v61
	v_and_b32_e32 v61, 0xffff0000, v61
	v_pk_mul_f32 v[64:65], v[64:65], v[60:61]
	v_lshlrev_b32_e32 v60, 16, v62
	v_and_b32_e32 v61, 0xffff0000, v62
	v_pk_mul_f32 v[68:69], v[68:69], v[60:61]
	v_lshlrev_b32_e32 v60, 16, v63
	v_and_b32_e32 v61, 0xffff0000, v63
	v_pk_mul_f32 v[62:63], v[74:75], v[70:71]
	v_mov_b32_e32 v57, s0
	v_pk_mul_f32 v[70:71], v[62:63], v[60:61]
	v_cvt_pk_bf16_f32 v62, v68, v69
	v_lshlrev_b32_e32 v68, 16, v38
	v_and_b32_e32 v69, 0xffff0000, v38
	v_mul_f32_e32 v38, 0xbfb8aa3b, v68
	v_exp_f32_e32 v38, v38
	v_mul_f32_e32 v55, 0xbfb8aa3b, v69
	v_cvt_pk_bf16_f32 v60, v52, v53
	v_lshlrev_b64 v[52:53], 12, v[72:73]
	v_exp_f32_e32 v55, v55
	v_lshl_add_u64 v[52:53], s[90:91], 0, v[52:53]
	v_lshl_add_u64 v[52:53], v[52:53], 0, s[10:11]
	v_cvt_pk_bf16_f32 v61, v64, v65
	v_cvt_pk_bf16_f32 v63, v70, v71
	v_lshl_add_u64 v[52:53], v[52:53], 0, v[0:1]
	v_add_f32_e32 v38, 1.0, v38
	flat_store_dwordx4 v[52:53], v[60:63] offset:3072
	v_rcp_f32_e32 v70, v38
	v_add_f32_e32 v38, 1.0, v55
	ds_read_b128 v[60:63], v58 offset:2304
	v_rcp_f32_e32 v71, v38
	v_lshlrev_b32_e32 v38, 16, v39
	v_and_b32_e32 v39, 0xffff0000, v39
	v_mul_f32_e32 v55, 0xbfb8aa3b, v38
	v_exp_f32_e32 v55, v55
	v_mul_f32_e32 v59, 0xbfb8aa3b, v39
	v_exp_f32_e32 v59, v59
	s_waitcnt lgkmcnt(0)
	v_lshlrev_b32_e32 v64, 16, v60
	v_and_b32_e32 v65, 0xffff0000, v60
	v_pk_mul_f32 v[68:69], v[70:71], v[68:69]
	v_add_f32_e32 v55, 1.0, v55
	v_pk_mul_f32 v[64:65], v[68:69], v[64:65]
	v_lshlrev_b32_e32 v68, 16, v40
	v_rcp_f32_e32 v70, v55
	v_add_f32_e32 v55, 1.0, v59
	v_and_b32_e32 v69, 0xffff0000, v40
	v_mul_f32_e32 v40, 0xbfb8aa3b, v68
	v_rcp_f32_e32 v71, v55
	v_exp_f32_e32 v40, v40
	v_mul_f32_e32 v55, 0xbfb8aa3b, v69
	v_exp_f32_e32 v55, v55
	v_pk_mul_f32 v[38:39], v[70:71], v[38:39]
	v_add_f32_e32 v40, 1.0, v40
	v_rcp_f32_e32 v70, v40
	v_add_f32_e32 v40, 1.0, v55
	v_rcp_f32_e32 v71, v40
	v_lshlrev_b32_e32 v40, 16, v41
	v_and_b32_e32 v41, 0xffff0000, v41
	v_mul_f32_e32 v55, 0xbfb8aa3b, v40
	v_exp_f32_e32 v55, v55
	v_mul_f32_e32 v59, 0xbfb8aa3b, v41
	v_exp_f32_e32 v59, v59
	v_pk_mul_f32 v[68:69], v[70:71], v[68:69]
	v_add_f32_e32 v55, 1.0, v55
	v_rcp_f32_e32 v70, v55
	v_add_f32_e32 v55, 1.0, v59
	v_rcp_f32_e32 v71, v55
	v_lshlrev_b32_e32 v60, 16, v61
	v_and_b32_e32 v61, 0xffff0000, v61
	v_pk_mul_f32 v[38:39], v[38:39], v[60:61]
	v_lshlrev_b32_e32 v60, 16, v62
	v_and_b32_e32 v61, 0xffff0000, v62
	v_pk_mul_f32 v[68:69], v[68:69], v[60:61]
	v_lshlrev_b32_e32 v60, 16, v63
	v_and_b32_e32 v61, 0xffff0000, v63
	v_pk_mul_f32 v[40:41], v[70:71], v[40:41]
	v_cvt_pk_bf16_f32 v62, v68, v69
	v_pk_mul_f32 v[40:41], v[40:41], v[60:61]
	v_cvt_pk_bf16_f32 v61, v38, v39
	v_lshlrev_b64 v[38:39], 12, v[56:57]
	v_lshlrev_b32_e32 v56, 16, v34
	v_lshl_add_u64 v[38:39], s[90:91], 0, v[38:39]
	v_and_b32_e32 v57, 0xffff0000, v34
	v_mul_f32_e32 v34, 0xbfb8aa3b, v56
	v_cvt_pk_bf16_f32 v63, v40, v41
	v_lshl_add_u64 v[38:39], v[38:39], 0, s[10:11]
	v_exp_f32_e32 v34, v34
	v_mul_f32_e32 v41, 0xbfb8aa3b, v57
	v_cvt_pk_bf16_f32 v60, v64, v65
	v_lshl_add_u64 v[38:39], v[38:39], 0, v[0:1]
	v_exp_f32_e32 v59, v41
	flat_store_dwordx4 v[38:39], v[60:63] offset:3072
	ds_read_b128 v[60:63], v58 offset:3456
	v_add_f32_e32 v34, 1.0, v34
	v_rcp_f32_e32 v64, v34
	v_add_f32_e32 v34, 1.0, v59
	v_rcp_f32_e32 v65, v34
	v_lshlrev_b32_e32 v34, 16, v35
	v_and_b32_e32 v35, 0xffff0000, v35
	v_mul_f32_e32 v59, 0xbfb8aa3b, v34
	s_waitcnt lgkmcnt(0)
	v_lshlrev_b32_e32 v40, 16, v60
	v_and_b32_e32 v41, 0xffff0000, v60
	v_exp_f32_e32 v59, v59
	v_mul_f32_e32 v60, 0xbfb8aa3b, v35
	v_exp_f32_e32 v60, v60
	v_pk_mul_f32 v[56:57], v[64:65], v[56:57]
	v_add_f32_e32 v59, 1.0, v59
	v_rcp_f32_e32 v64, v59
	v_add_f32_e32 v59, 1.0, v60
	v_rcp_f32_e32 v65, v59
	v_lshlrev_b32_e32 v60, 16, v36
	v_pk_mul_f32 v[40:41], v[56:57], v[40:41]
	v_lshlrev_b32_e32 v56, 16, v61
	v_and_b32_e32 v57, 0xffff0000, v61
	v_pk_mul_f32 v[34:35], v[64:65], v[34:35]
	v_and_b32_e32 v61, 0xffff0000, v36
	v_mul_f32_e32 v36, 0xbfb8aa3b, v60
	v_pk_mul_f32 v[34:35], v[34:35], v[56:57]
	v_exp_f32_e32 v36, v36
	v_mul_f32_e32 v57, 0xbfb8aa3b, v61
	v_exp_f32_e32 v59, v57
	v_lshlrev_b32_e32 v56, 16, v62
	v_add_f32_e32 v36, 1.0, v36
	v_rcp_f32_e32 v64, v36
	v_add_f32_e32 v36, 1.0, v59
	v_rcp_f32_e32 v65, v36
	v_lshlrev_b32_e32 v36, 16, v37
	v_and_b32_e32 v37, 0xffff0000, v37
	v_mul_f32_e32 v59, 0xbfb8aa3b, v36
	v_and_b32_e32 v57, 0xffff0000, v62
	v_exp_f32_e32 v59, v59
	v_mul_f32_e32 v62, 0xbfb8aa3b, v37
	v_exp_f32_e32 v62, v62
	v_pk_mul_f32 v[60:61], v[64:65], v[60:61]
	v_add_f32_e32 v59, 1.0, v59
	v_rcp_f32_e32 v64, v59
	v_add_f32_e32 v59, 1.0, v62
	v_rcp_f32_e32 v65, v59
	v_mov_b32_e32 v55, s0
	v_pk_mul_f32 v[56:57], v[60:61], v[56:57]
	v_lshlrev_b32_e32 v60, 16, v63
	v_and_b32_e32 v61, 0xffff0000, v63
	v_pk_mul_f32 v[36:37], v[64:65], v[36:37]
	v_cvt_pk_bf16_f32 v62, v56, v57
	v_pk_mul_f32 v[36:37], v[36:37], v[60:61]
	v_cvt_pk_bf16_f32 v61, v34, v35
	v_lshlrev_b64 v[34:35], 12, v[54:55]
	v_lshl_add_u64 v[34:35], s[90:91], 0, v[34:35]
	v_lshl_add_u64 v[34:35], v[34:35], 0, s[10:11]
	v_cvt_pk_bf16_f32 v60, v40, v41
	v_cvt_pk_bf16_f32 v63, v36, v37
	v_lshl_add_u64 v[36:37], v[34:35], 0, v[0:1]
	flat_store_dwordx4 v[36:37], v[60:63] offset:3072
	ds_write2_b64 v197, v[18:19], v[20:21] offset1:2
	v_pk_mul_f32 v[18:19], v[26:27], v[66:67] op_sel_hi:[1,0]
	v_pk_mul_f32 v[20:21], v[28:29], v[66:67] op_sel_hi:[1,0]
	ds_write2_b64 v197, v[2:3], v[4:5] offset0:8 offset1:10
	v_pk_mul_f32 v[2:3], v[10:11], v[66:67] op_sel_hi:[1,0]
	v_pk_mul_f32 v[4:5], v[12:13], v[66:67] op_sel_hi:[1,0]
	v_cvt_pk_bf16_f32 v18, v18, v19
	v_cvt_pk_bf16_f32 v19, v20, v21
	v_pk_mul_f32 v[20:21], v[30:31], v[66:67] op_sel_hi:[1,0]
	v_cvt_pk_bf16_f32 v2, v2, v3
	v_cvt_pk_bf16_f32 v3, v4, v5
	v_pk_mul_f32 v[4:5], v[14:15], v[66:67] op_sel_hi:[1,0]
	v_cvt_pk_bf16_f32 v20, v20, v21
	v_cvt_pk_bf16_f32 v21, v22, v23
	v_cvt_pk_bf16_f32 v4, v4, v5
	v_cvt_pk_bf16_f32 v5, v6, v7
	ds_write2_b64 v197, v[18:19], v[20:21] offset0:4 offset1:6
	ds_write2_b64 v197, v[2:3], v[4:5] offset0:12 offset1:14
	v_lshlrev_b32_e32 v0, 1, v174
	s_waitcnt lgkmcnt(0)
	v_lshl_add_u64 v[2:3], v[42:43], 0, v[0:1]
	v_mov_b32_e32 v10, v216
	v_mov_b32_e32 v11, v217
	v_mov_b32_e32 v12, v218
	v_mov_b32_e32 v13, v219
	v_lshl_add_u64 v[2:3], v[48:49], 0, v[0:1]
	v_mov_b32_e32 v14, v220
	v_mov_b32_e32 v15, v221
	v_mov_b32_e32 v16, v222
	v_mov_b32_e32 v17, v223
	v_lshl_add_u64 v[2:3], v[44:45], 0, v[0:1]
	v_lshl_add_u64 v[4:5], v[46:47], 0, v[0:1]
	ds_read_b128 v[18:21], v58
	v_mov_b32_e32 v6, v224
	v_mov_b32_e32 v7, v225
	v_mov_b32_e32 v8, v226
	v_mov_b32_e32 v9, v227
	s_nop 0
	v_mov_b32_e32 v2, v228
	v_mov_b32_e32 v3, v229
	v_mov_b32_e32 v4, v230
	v_mov_b32_e32 v5, v231
	s_mov_b64 s[0:1], 0xc00
	v_lshl_add_u64 v[48:49], v[34:35], 0, s[0:1]
	s_waitcnt lgkmcnt(0)
	v_lshlrev_b32_e32 v22, 16, v18
	v_and_b32_e32 v23, 0xffff0000, v18
	s_waitcnt vmcnt(4)
	v_lshlrev_b32_e32 v24, 16, v10
	v_and_b32_e32 v25, 0xffff0000, v10
	v_mul_f32_e32 v0, 0xbfb8aa3b, v24
	v_exp_f32_e32 v0, v0
	v_mul_f32_e32 v10, 0xbfb8aa3b, v25
	v_exp_f32_e32 v10, v10
	v_add_f32_e32 v0, 1.0, v0
	v_rcp_f32_e32 v26, v0
	v_add_f32_e32 v0, 1.0, v10
	v_lshlrev_b32_e32 v10, 16, v11
	v_rcp_f32_e32 v27, v0
	v_and_b32_e32 v11, 0xffff0000, v11
	v_mul_f32_e32 v0, 0xbfb8aa3b, v10
	v_exp_f32_e32 v0, v0
	v_mul_f32_e32 v18, 0xbfb8aa3b, v11
	v_exp_f32_e32 v18, v18
	v_pk_mul_f32 v[24:25], v[26:27], v[24:25]
	v_add_f32_e32 v0, 1.0, v0
	v_rcp_f32_e32 v26, v0
	v_add_f32_e32 v0, 1.0, v18
	v_rcp_f32_e32 v27, v0
	v_pk_mul_f32 v[22:23], v[24:25], v[22:23]
	v_lshlrev_b32_e32 v24, 16, v12
	v_lshlrev_b32_e32 v18, 16, v19
	v_and_b32_e32 v19, 0xffff0000, v19
	v_pk_mul_f32 v[10:11], v[26:27], v[10:11]
	v_and_b32_e32 v25, 0xffff0000, v12
	v_mul_f32_e32 v0, 0xbfb8aa3b, v24
	v_pk_mul_f32 v[18:19], v[10:11], v[18:19]
	v_exp_f32_e32 v0, v0
	v_mul_f32_e32 v11, 0xbfb8aa3b, v25
	v_exp_f32_e32 v12, v11
	v_lshlrev_b32_e32 v10, 16, v20
	v_add_f32_e32 v0, 1.0, v0
	v_rcp_f32_e32 v26, v0
	v_add_f32_e32 v0, 1.0, v12
	v_lshlrev_b32_e32 v12, 16, v13
	v_rcp_f32_e32 v27, v0
	v_and_b32_e32 v13, 0xffff0000, v13
	v_mul_f32_e32 v0, 0xbfb8aa3b, v12
	v_and_b32_e32 v11, 0xffff0000, v20
	v_exp_f32_e32 v0, v0
	v_mul_f32_e32 v20, 0xbfb8aa3b, v13
	v_exp_f32_e32 v20, v20
	v_pk_mul_f32 v[24:25], v[26:27], v[24:25]
	v_add_f32_e32 v0, 1.0, v0
	v_rcp_f32_e32 v26, v0
	v_add_f32_e32 v0, 1.0, v20
	v_rcp_f32_e32 v27, v0
	v_pk_mul_f32 v[24:25], v[24:25], v[10:11]
	v_lshlrev_b32_e32 v10, 16, v21
	v_and_b32_e32 v11, 0xffff0000, v21
	v_pk_mul_f32 v[12:13], v[26:27], v[12:13]
	s_nop 0
	v_pk_mul_f32 v[20:21], v[12:13], v[10:11]
	v_cvt_pk_bf16_f32 v10, v22, v23
	v_cvt_pk_bf16_f32 v13, v20, v21
	v_lshlrev_b32_e32 v20, 16, v14
	v_and_b32_e32 v21, 0xffff0000, v14
	v_mul_f32_e32 v0, 0xbfb8aa3b, v20
	v_cvt_pk_bf16_f32 v11, v18, v19
	v_cvt_pk_bf16_f32 v12, v24, v25
	v_exp_f32_e32 v0, v0
	v_mul_f32_e32 v14, 0xbfb8aa3b, v21
	flat_store_dwordx4 v[50:51], v[10:13] offset:3200
	v_exp_f32_e32 v14, v14
	ds_read_b128 v[10:13], v58 offset:1152
	v_add_f32_e32 v0, 1.0, v0
	v_rcp_f32_e32 v22, v0
	v_add_f32_e32 v0, 1.0, v14
	v_lshlrev_b32_e32 v14, 16, v15
	v_rcp_f32_e32 v23, v0
	v_and_b32_e32 v15, 0xffff0000, v15
	v_mul_f32_e32 v0, 0xbfb8aa3b, v14
	s_waitcnt lgkmcnt(0)
	v_lshlrev_b32_e32 v18, 16, v10
	v_and_b32_e32 v19, 0xffff0000, v10
	v_exp_f32_e32 v0, v0
	v_mul_f32_e32 v10, 0xbfb8aa3b, v15
	v_exp_f32_e32 v10, v10
	v_pk_mul_f32 v[20:21], v[22:23], v[20:21]
	v_add_f32_e32 v0, 1.0, v0
	v_rcp_f32_e32 v22, v0
	v_add_f32_e32 v0, 1.0, v10
	v_rcp_f32_e32 v23, v0
	v_pk_mul_f32 v[18:19], v[20:21], v[18:19]
	v_lshlrev_b32_e32 v20, 16, v16
	v_lshlrev_b32_e32 v10, 16, v11
	v_and_b32_e32 v11, 0xffff0000, v11
	v_pk_mul_f32 v[14:15], v[22:23], v[14:15]
	v_and_b32_e32 v21, 0xffff0000, v16
	v_mul_f32_e32 v0, 0xbfb8aa3b, v20
	v_pk_mul_f32 v[14:15], v[14:15], v[10:11]
	v_exp_f32_e32 v0, v0
	v_mul_f32_e32 v11, 0xbfb8aa3b, v21
	v_exp_f32_e32 v16, v11
	v_lshlrev_b32_e32 v10, 16, v12
	v_add_f32_e32 v0, 1.0, v0
	v_rcp_f32_e32 v22, v0
	v_add_f32_e32 v0, 1.0, v16
	v_lshlrev_b32_e32 v16, 16, v17
	v_rcp_f32_e32 v23, v0
	v_and_b32_e32 v17, 0xffff0000, v17
	v_mul_f32_e32 v0, 0xbfb8aa3b, v16
	v_and_b32_e32 v11, 0xffff0000, v12
	v_exp_f32_e32 v0, v0
	v_mul_f32_e32 v12, 0xbfb8aa3b, v17
	v_exp_f32_e32 v12, v12
	v_pk_mul_f32 v[20:21], v[22:23], v[20:21]
	v_add_f32_e32 v0, 1.0, v0
	v_rcp_f32_e32 v22, v0
	v_add_f32_e32 v0, 1.0, v12
	v_rcp_f32_e32 v23, v0
	v_pk_mul_f32 v[20:21], v[20:21], v[10:11]
	v_lshlrev_b32_e32 v10, 16, v13
	v_and_b32_e32 v11, 0xffff0000, v13
	v_pk_mul_f32 v[12:13], v[22:23], v[16:17]
	s_nop 0
	v_pk_mul_f32 v[16:17], v[12:13], v[10:11]
	v_cvt_pk_bf16_f32 v10, v18, v19
	v_cvt_pk_bf16_f32 v13, v16, v17
	v_lshlrev_b32_e32 v16, 16, v6
	v_and_b32_e32 v17, 0xffff0000, v6
	v_mul_f32_e32 v0, 0xbfb8aa3b, v16
	v_cvt_pk_bf16_f32 v11, v14, v15
	v_cvt_pk_bf16_f32 v12, v20, v21
	v_exp_f32_e32 v0, v0
	v_mul_f32_e32 v6, 0xbfb8aa3b, v17
	flat_store_dwordx4 v[52:53], v[10:13] offset:3200
	v_exp_f32_e32 v6, v6
	ds_read_b128 v[10:13], v58 offset:2304
	v_add_f32_e32 v0, 1.0, v0
	v_rcp_f32_e32 v18, v0
	v_add_f32_e32 v0, 1.0, v6
	v_lshlrev_b32_e32 v6, 16, v7
	v_rcp_f32_e32 v19, v0
	v_and_b32_e32 v7, 0xffff0000, v7
	v_mul_f32_e32 v0, 0xbfb8aa3b, v6
	s_waitcnt lgkmcnt(0)
	v_lshlrev_b32_e32 v14, 16, v10
	v_and_b32_e32 v15, 0xffff0000, v10
	v_exp_f32_e32 v0, v0
	v_mul_f32_e32 v10, 0xbfb8aa3b, v7
	v_exp_f32_e32 v10, v10
	v_pk_mul_f32 v[16:17], v[18:19], v[16:17]
	v_add_f32_e32 v0, 1.0, v0
	v_rcp_f32_e32 v18, v0
	v_add_f32_e32 v0, 1.0, v10
	v_rcp_f32_e32 v19, v0
	v_pk_mul_f32 v[14:15], v[16:17], v[14:15]
	v_lshlrev_b32_e32 v16, 16, v8
	v_lshlrev_b32_e32 v10, 16, v11
	v_and_b32_e32 v11, 0xffff0000, v11
	v_pk_mul_f32 v[6:7], v[18:19], v[6:7]
	v_and_b32_e32 v17, 0xffff0000, v8
	v_mul_f32_e32 v0, 0xbfb8aa3b, v16
	v_pk_mul_f32 v[10:11], v[6:7], v[10:11]
	v_exp_f32_e32 v0, v0
	v_mul_f32_e32 v7, 0xbfb8aa3b, v17
	v_exp_f32_e32 v8, v7
	v_lshlrev_b32_e32 v6, 16, v12
	v_add_f32_e32 v0, 1.0, v0
	v_rcp_f32_e32 v18, v0
	v_add_f32_e32 v0, 1.0, v8
	v_lshlrev_b32_e32 v8, 16, v9
	v_rcp_f32_e32 v19, v0
	v_and_b32_e32 v9, 0xffff0000, v9
	v_mul_f32_e32 v0, 0xbfb8aa3b, v8
	v_and_b32_e32 v7, 0xffff0000, v12
	v_exp_f32_e32 v0, v0
	v_mul_f32_e32 v12, 0xbfb8aa3b, v9
	v_exp_f32_e32 v12, v12
	v_pk_mul_f32 v[16:17], v[18:19], v[16:17]
	v_add_f32_e32 v0, 1.0, v0
	v_rcp_f32_e32 v18, v0
	v_add_f32_e32 v0, 1.0, v12
	v_rcp_f32_e32 v19, v0
	v_pk_mul_f32 v[16:17], v[16:17], v[6:7]
	v_lshlrev_b32_e32 v6, 16, v13
	v_and_b32_e32 v7, 0xffff0000, v13
	v_pk_mul_f32 v[8:9], v[18:19], v[8:9]
	s_nop 0
	v_pk_mul_f32 v[12:13], v[8:9], v[6:7]
	v_cvt_pk_bf16_f32 v6, v14, v15
	v_cvt_pk_bf16_f32 v9, v12, v13
	v_lshlrev_b32_e32 v12, 16, v2
	v_and_b32_e32 v13, 0xffff0000, v2
	v_mul_f32_e32 v0, 0xbfb8aa3b, v12
	v_cvt_pk_bf16_f32 v7, v10, v11
	v_cvt_pk_bf16_f32 v8, v16, v17
	v_exp_f32_e32 v0, v0
	v_mul_f32_e32 v2, 0xbfb8aa3b, v13
	flat_store_dwordx4 v[38:39], v[6:9] offset:3200
	v_exp_f32_e32 v2, v2
	ds_read_b128 v[6:9], v58 offset:3456
	v_add_f32_e32 v0, 1.0, v0
	v_rcp_f32_e32 v14, v0
	v_add_f32_e32 v0, 1.0, v2
	v_lshlrev_b32_e32 v2, 16, v3
	v_rcp_f32_e32 v15, v0
	v_and_b32_e32 v3, 0xffff0000, v3
	v_mul_f32_e32 v0, 0xbfb8aa3b, v2
	s_waitcnt lgkmcnt(0)
	v_lshlrev_b32_e32 v10, 16, v6
	v_and_b32_e32 v11, 0xffff0000, v6
	v_exp_f32_e32 v0, v0
	v_mul_f32_e32 v6, 0xbfb8aa3b, v3
	v_exp_f32_e32 v6, v6
	v_pk_mul_f32 v[12:13], v[14:15], v[12:13]
	v_add_f32_e32 v0, 1.0, v0
	v_rcp_f32_e32 v14, v0
	v_add_f32_e32 v0, 1.0, v6
	v_rcp_f32_e32 v15, v0
	v_pk_mul_f32 v[10:11], v[12:13], v[10:11]
	v_lshlrev_b32_e32 v12, 16, v4
	v_lshlrev_b32_e32 v6, 16, v7
	v_and_b32_e32 v7, 0xffff0000, v7
	v_pk_mul_f32 v[2:3], v[14:15], v[2:3]
	v_and_b32_e32 v13, 0xffff0000, v4
	v_mul_f32_e32 v0, 0xbfb8aa3b, v12
	v_pk_mul_f32 v[6:7], v[2:3], v[6:7]
	v_exp_f32_e32 v0, v0
	v_mul_f32_e32 v3, 0xbfb8aa3b, v13
	v_exp_f32_e32 v4, v3
	v_lshlrev_b32_e32 v2, 16, v8
	v_add_f32_e32 v0, 1.0, v0
	v_rcp_f32_e32 v14, v0
	v_add_f32_e32 v0, 1.0, v4
	v_lshlrev_b32_e32 v4, 16, v5
	v_rcp_f32_e32 v15, v0
	v_and_b32_e32 v5, 0xffff0000, v5
	v_mul_f32_e32 v0, 0xbfb8aa3b, v4
	v_and_b32_e32 v3, 0xffff0000, v8
	v_exp_f32_e32 v0, v0
	v_mul_f32_e32 v8, 0xbfb8aa3b, v5
	v_exp_f32_e32 v8, v8
	v_pk_mul_f32 v[12:13], v[14:15], v[12:13]
	v_add_f32_e32 v0, 1.0, v0
	v_rcp_f32_e32 v14, v0
	v_add_f32_e32 v0, 1.0, v8
	v_rcp_f32_e32 v15, v0
	v_pk_mul_f32 v[12:13], v[12:13], v[2:3]
	v_lshlrev_b32_e32 v2, 16, v9
	v_and_b32_e32 v3, 0xffff0000, v9
	v_pk_mul_f32 v[4:5], v[14:15], v[4:5]
	s_nop 0
	v_pk_mul_f32 v[8:9], v[4:5], v[2:3]
	v_cvt_pk_bf16_f32 v2, v10, v11
	v_cvt_pk_bf16_f32 v3, v6, v7
	v_cvt_pk_bf16_f32 v4, v12, v13
	v_cvt_pk_bf16_f32 v5, v8, v9
	s_cbranch_execnz .Ltail_nc

.Ltail_nc:
	v_lshlrev_b32_e32 v0, 1, v166
	s_cmp_lt_i32 s7, 0
	v_lshl_add_u64 v[6:7], v[48:49], 0, v[0:1]
	s_cselect_b64 s[4:5], -1, 0
	s_waitcnt lgkmcnt(0)
	flat_store_dwordx4 v[6:7], v[2:5] offset:128
	s_branch .LBB0_348
